# MLP1: next tile's k-tile 0 slabs + row sum-of-squares prefetched into spare VGPRs at k-loop exit (before the epilogue stores); prologue waits vmcnt(16) instead of queueing behind the store burst
# baseline (speedup 1.0000x reference)
_Z14fwd_megakernel6Params:
	s_mov_b32 s12, 0
	s_nop 0
	v_writelane_b32 v255, s12, 43
	s_load_dwordx8 s[4:11], s[0:1], 0x80
	v_and_b32_e32 v204, 0x3ff, v0
	v_writelane_b32 v250, s2, 0
	s_add_u32 s2, s0, 0xb0
	s_addc_u32 s3, s1, 0
	s_waitcnt lgkmcnt(0)
	v_writelane_b32 v250, s4, 1
	v_readfirstlane_b32 s16, v204
	s_nop 0
	v_writelane_b32 v250, s5, 2
	v_writelane_b32 v250, s6, 3
	v_writelane_b32 v250, s7, 4
	v_writelane_b32 v250, s8, 5
	v_writelane_b32 v250, s9, 6
	v_writelane_b32 v250, s10, 7
	v_writelane_b32 v250, s11, 8
	s_load_dword s44, s[0:1], 0xb8
	s_load_dwordx4 s[4:7], s[0:1], 0xa0
	s_waitcnt lgkmcnt(0)
	v_writelane_b32 v250, s4, 9
	s_nop 1
	v_writelane_b32 v250, s5, 10
	v_writelane_b32 v250, s6, 11
	v_writelane_b32 v250, s7, 12
	s_load_dwordx2 s[4:5], s[0:1], 0xb0
	v_cmp_eq_u32_e64 s[6:7], 0, v204
	s_waitcnt lgkmcnt(0)
	v_writelane_b32 v250, s4, 13
	s_nop 1
	v_writelane_b32 v250, s5, 14
	s_mov_b64 s[4:5], exec
	v_writelane_b32 v250, s6, 15
	s_nop 1
	v_writelane_b32 v250, s7, 16
	s_and_b64 s[6:7], s[4:5], s[6:7]
	s_mov_b64 exec, s[6:7]
	s_cbranch_execz .LBB0_2
	v_mov_b32_e32 v2, 0
	v_mov_b32_e32 v3, v2
	v_mov_b32_e32 v4, v2
	v_mov_b32_e32 v5, v2
	v_mov_b32_e32 v1, 0x21400
	ds_write_b128 v1, v[2:5]

.LBB0_1602:
	s_and_b32 s0, s35, 3
	s_lshl_b32 s0, s0, 2
	s_bfe_u32 s6, s35, 0x20003
	s_or_b32 s6, s6, s0
	s_bfe_u32 s0, s35, 0x30005
	s_bfe_u32 s1, s35, 0x10002
	s_lshl_b32 s1, s1, 3
	s_or_b32 s0, s0, s1
	s_lshr_b32 s1, s35, 8
	s_lshl_b32 s1, s1, 4
	s_or_b32 s0, s0, s1
	s_lshl_b32 s4, s0, 8
	s_ashr_i32 s5, s4, 31
	s_ashr_i32 s7, s6, 31
	s_lshl_b64 s[0:1], s[6:7], 19
	s_lshl_b64 s[8:9], s[4:5], 11
	v_readlane_b32 s10, v250, 44
	v_readlane_b32 s11, v250, 45
	s_add_u32 s10, s10, s8
	v_mov_b32_e32 v34, v172
	s_addc_u32 s11, s11, s9
	s_add_u32 s12, s31, s0
	v_lshlrev_b32_e32 v0, 4, v34
	v_ashrrev_i32_e32 v35, 3, v34
	v_and_b32_e32 v0, 0x70, v0
	s_addc_u32 s13, s34, s1
	v_lshl_or_b32 v0, v35, 11, v0
	v_lshrrev_b32_e32 v36, 1, v35
	v_xor_b32_e32 v36, v36, v34
	v_lshlrev_b32_e32 v36, 4, v36
	v_lshlrev_b32_e32 v37, 7, v35
	v_and_or_b32 v194, v36, s55, v37
	v_add_u32_e32 v195, 0x10000, v194
	v_readlane_b32 s14, v255, 43
	s_nop 0
	s_cmp_lg_u32 s14, 0
	s_cbranch_scc1 .Lpf_mlp1_have
	v_lshl_add_u64 v[26:27], s[12:13], 0, v[0:1]
	v_add_co_u32_e32 v10, vcc, s52, v26
	v_lshl_add_u64 v[28:29], s[10:11], 0, v[0:1]
	s_nop 0
	v_addc_co_u32_e32 v11, vcc, 0, v27, vcc
	v_add_co_u32_e32 v14, vcc, s52, v28
	global_load_dwordx4 v[216:219], v0, s[12:13]
	global_load_dwordx4 v[220:223], v0, s[10:11]
	v_addc_co_u32_e32 v15, vcc, 0, v29, vcc
	v_add_co_u32_e32 v18, vcc, s56, v26
	global_load_dwordx4 v[224:227], v[10:11], off
	s_nop 0
	global_load_dwordx4 v[228:231], v[14:15], off
	v_addc_co_u32_e32 v19, vcc, 0, v27, vcc
	v_add_co_u32_e32 v22, vcc, s56, v28
	v_lshrrev_b32_e32 v36, 1, v35
	s_nop 0
	v_addc_co_u32_e32 v23, vcc, 0, v29, vcc
	v_add_co_u32_e32 v26, vcc, s57, v26
	global_load_dwordx4 v[232:235], v[18:19], off
	s_nop 0
	global_load_dwordx4 v[236:239], v[22:23], off
	v_addc_co_u32_e32 v27, vcc, 0, v27, vcc
	v_add_co_u32_e32 v30, vcc, s57, v28
	v_xor_b32_e32 v34, v36, v34
	s_nop 0
	v_addc_co_u32_e32 v31, vcc, 0, v29, vcc
	global_load_dwordx4 v[240:243], v[26:27], off
	s_nop 0
	global_load_dwordx4 v[244:247], v[30:31], off
	v_lshlrev_b32_e32 v35, 7, v35
	v_lshlrev_b32_e32 v34, 4, v34
	v_and_or_b32 v194, v34, s55, v35
	v_add_u32_e32 v195, 0x10000, v194
	s_waitcnt vmcnt(0)
	s_branch .Lpf_mlp1_wr
.Lpf_mlp1_have:
	s_waitcnt vmcnt(16)
.Lpf_mlp1_wr:
	ds_write_b128 v194, v[216:219]
	ds_write_b128 v195, v[220:223]
	ds_write_b128 v194, v[224:227] offset:8192
	ds_write_b128 v195, v[228:231] offset:8192
	ds_write_b128 v194, v[232:235] offset:16384
	ds_write_b128 v195, v[236:239] offset:16384
	ds_write_b128 v194, v[240:243] offset:24576
	ds_write_b128 v195, v[244:247] offset:24576
	s_waitcnt lgkmcnt(0)
	s_barrier
	s_and_saveexec_b64 s[10:11], s[2:3]
	s_cbranch_execz .LBB0_1604
	s_cmp_lg_u32 s14, 0
	s_cbranch_scc1 .Lpf_mlp1_sq
	v_add_u32_e32 v2, s4, v172
	v_ashrrev_i32_e32 v3, 31, v2
	v_readlane_b32 s12, v250, 46
	v_lshlrev_b64 v[2:3], 6, v[2:3]
	v_readlane_b32 s13, v250, 47
	s_nop 1
	v_lshl_add_u64 v[14:15], s[12:13], 0, v[2:3]
	global_load_dwordx4 v[164:167], v[14:15], off
	global_load_dwordx4 v[168:171], v[14:15], off offset:16
	global_load_dwordx4 v[196:199], v[14:15], off offset:32
	s_nop 0
	global_load_dwordx4 v[200:203], v[14:15], off offset:48
	s_waitcnt vmcnt(0)
.Lpf_mlp1_sq:
	v_mov_b64_e32 v[2:3], v[164:165]
	v_mov_b64_e32 v[4:5], v[166:167]
	v_mov_b64_e32 v[6:7], v[168:169]
	v_mov_b64_e32 v[8:9], v[170:171]
	v_mov_b64_e32 v[10:11], v[196:197]
	v_mov_b64_e32 v[12:13], v[198:199]
	v_mov_b64_e32 v[14:15], v[200:201]
	v_mov_b64_e32 v[16:17], v[202:203]
	v_mov_b32_e32 v18, v2
	v_mov_b32_e32 v19, v6
	v_mov_b32_e32 v6, v3
	v_mov_b32_e32 v2, v4
	v_mov_b32_e32 v3, v8
	v_mov_b32_e32 v8, v5
	v_mov_b32_e32 v4, v10
	v_mov_b32_e32 v5, v14
	v_mov_b32_e32 v14, v11
	v_pk_add_f32 v[6:7], v[18:19], v[6:7]
	v_mov_b32_e32 v10, v12
	v_mov_b32_e32 v11, v16
	v_pk_add_f32 v[4:5], v[4:5], v[14:15]
	v_pk_add_f32 v[2:3], v[2:3], v[6:7]
	v_mov_b32_e32 v16, v13
	v_pk_add_f32 v[4:5], v[10:11], v[4:5]
	v_pk_add_f32 v[2:3], v[8:9], v[2:3]
	v_pk_add_f32 v[4:5], v[16:17], v[4:5]
	v_add_f32_e32 v2, v2, v3
	v_add_f32_e32 v2, v2, v4
	v_add_f32_e32 v2, v2, v5
	v_fmamk_f32 v2, v2, 0x3a800000, v206
	v_mul_f32_e32 v3, 0x4b800000, v2
	v_cmp_gt_f32_e32 vcc, s58, v2
	s_nop 1
	v_cndmask_b32_e32 v2, v2, v3, vcc
	v_rsq_f32_e32 v2, v2
	s_nop 0
	v_mul_f32_e32 v3, 0x45800000, v2
	v_cndmask_b32_e32 v2, v2, v3, vcc
	ds_write_b32 v178, v2

.Lg_mlp1_join:
	ds_read_b128 v[154:157], v187 offset:32768
	ds_read_b128 v[162:165], v191
	ds_read_b128 v[158:161], v187 offset:36864
	ds_read_b128 v[166:169], v191 offset:4096
	ds_read_b128 v[196:199], v191 offset:8192
	ds_read_b128 v[200:203], v191 offset:12288
	s_waitcnt lgkmcnt(6)
	v_mfma_f32_32x32x16_bf16 v[98:113], v[130:133], v[138:141], v[98:113]
	s_add_u32 s8, s8, 0x80
	s_addc_u32 s9, s9, 0
	v_mfma_f32_32x32x16_bf16 v[114:129], v[134:137], v[138:141], v[114:129]
	s_add_u32 s10, s10, 0x80
	s_addc_u32 s11, s11, 0
	v_mfma_f32_32x32x16_bf16 v[82:97], v[130:133], v[142:145], v[82:97]
	s_add_u32 s12, s12, 0x80
	s_addc_u32 s13, s13, 0
	v_mfma_f32_32x32x16_bf16 v[66:81], v[134:137], v[142:145], v[66:81]
	s_add_u32 s14, s14, 0x80
	s_addc_u32 s15, s15, 0
	v_mfma_f32_32x32x16_bf16 v[50:65], v[130:133], v[146:149], v[50:65]
	s_add_u32 s16, s16, 0x80
	s_addc_u32 s17, s17, 0
	v_mfma_f32_32x32x16_bf16 v[34:49], v[134:137], v[146:149], v[34:49]
	s_add_u32 s18, s18, 0x80
	s_addc_u32 s19, s19, 0
	v_mfma_f32_32x32x16_bf16 v[18:33], v[130:133], v[150:153], v[18:33]
	s_add_u32 s20, s20, 0x80
	s_addc_u32 s21, s21, 0
	v_mfma_f32_32x32x16_bf16 v[2:17], v[134:137], v[150:153], v[2:17]
	s_add_u32 s22, s22, 0x80
	s_addc_u32 s23, s23, 0
	ds_read_b128 v[130:133], v188 offset:32768
	ds_read_b128 v[138:141], v192
	ds_read_b128 v[134:137], v188 offset:36864
	ds_read_b128 v[142:145], v192 offset:4096
	ds_read_b128 v[146:149], v192 offset:8192
	ds_read_b128 v[150:153], v192 offset:12288
	s_waitcnt lgkmcnt(6)
	v_mfma_f32_32x32x16_bf16 v[98:113], v[154:157], v[162:165], v[98:113]
	v_mfma_f32_32x32x16_bf16 v[114:129], v[158:161], v[162:165], v[114:129]
	v_mfma_f32_32x32x16_bf16 v[82:97], v[154:157], v[166:169], v[82:97]
	v_mfma_f32_32x32x16_bf16 v[66:81], v[158:161], v[166:169], v[66:81]
	v_mfma_f32_32x32x16_bf16 v[50:65], v[154:157], v[196:199], v[50:65]
	v_mfma_f32_32x32x16_bf16 v[34:49], v[158:161], v[196:199], v[34:49]
	v_mfma_f32_32x32x16_bf16 v[18:33], v[154:157], v[200:203], v[18:33]
	v_mfma_f32_32x32x16_bf16 v[2:17], v[158:161], v[200:203], v[2:17]
	ds_read_b128 v[154:157], v189 offset:32768
	ds_read_b128 v[162:165], v193
	ds_read_b128 v[158:161], v189 offset:36864
	ds_read_b128 v[166:169], v193 offset:4096
	ds_read_b128 v[196:199], v193 offset:8192
	ds_read_b128 v[200:203], v193 offset:12288
	s_waitcnt lgkmcnt(6)
	v_mfma_f32_32x32x16_bf16 v[98:113], v[130:133], v[138:141], v[98:113]
	v_mfma_f32_32x32x16_bf16 v[114:129], v[134:137], v[138:141], v[114:129]
	v_mfma_f32_32x32x16_bf16 v[82:97], v[130:133], v[142:145], v[82:97]
	v_mfma_f32_32x32x16_bf16 v[66:81], v[134:137], v[142:145], v[66:81]
	v_mfma_f32_32x32x16_bf16 v[50:65], v[130:133], v[146:149], v[50:65]
	v_mfma_f32_32x32x16_bf16 v[34:49], v[134:137], v[146:149], v[34:49]
	v_mfma_f32_32x32x16_bf16 v[18:33], v[130:133], v[150:153], v[18:33]
	v_mfma_f32_32x32x16_bf16 v[2:17], v[134:137], v[150:153], v[2:17]
	s_waitcnt vmcnt(0) lgkmcnt(0)
	s_barrier
	s_add_i32 s5, s5, 2
	s_cmp_lt_u32 s5, 16
	s_cbranch_scc1 .Lg_mlp1_top
	v_mfma_f32_32x32x16_bf16 v[98:113], v[154:157], v[162:165], v[98:113]
	v_mfma_f32_32x32x16_bf16 v[114:129], v[158:161], v[162:165], v[114:129]
	v_mfma_f32_32x32x16_bf16 v[82:97], v[154:157], v[166:169], v[82:97]
	v_mfma_f32_32x32x16_bf16 v[66:81], v[158:161], v[166:169], v[66:81]
	v_mfma_f32_32x32x16_bf16 v[50:65], v[154:157], v[196:199], v[50:65]
	v_mfma_f32_32x32x16_bf16 v[34:49], v[158:161], v[196:199], v[34:49]
	v_mfma_f32_32x32x16_bf16 v[18:33], v[154:157], v[200:203], v[18:33]
	v_mfma_f32_32x32x16_bf16 v[2:17], v[158:161], v[200:203], v[2:17]
	v_readlane_b32 s26, v250, 13
	s_mov_b32 s27, 0
	s_nop 0
	s_add_i32 s26, s35, s26
	s_cmpk_gt_i32 s26, 0x3ff
	s_cbranch_scc1 .Lg_mlp1_nopf
	s_mov_b32 s27, 1
	v_lshrrev_b32_e32 v248, 3, v204
	v_and_b32_e32 v249, 7, v204
	v_lshlrev_b32_e32 v249, 4, v249
	v_lshl_or_b32 v248, v248, 11, v249
	s_add_u32 s16, s16, 0x800000
	s_addc_u32 s17, s17, 0
	s_add_u32 s18, s18, 0x800000
	s_addc_u32 s19, s19, 0
	s_add_u32 s20, s20, 0x800000
	s_addc_u32 s21, s21, 0
	s_add_u32 s22, s22, 0x800000
	s_addc_u32 s23, s23, 0
	global_load_dwordx4 v[216:219], v248, s[8:9] offset:-2176
	global_load_dwordx4 v[220:223], v248, s[16:17] offset:-2176
	global_load_dwordx4 v[224:227], v248, s[10:11] offset:-2176
	global_load_dwordx4 v[228:231], v248, s[18:19] offset:-2176
	global_load_dwordx4 v[232:235], v248, s[12:13] offset:-2176
	global_load_dwordx4 v[236:239], v248, s[20:21] offset:-2176
	global_load_dwordx4 v[240:243], v248, s[14:15] offset:-2176
	global_load_dwordx4 v[244:247], v248, s[22:23] offset:-2176
	s_and_saveexec_b64 s[28:29], s[2:3]
	v_add_u32_e32 v249, s4, v204
	v_add_u32_e32 v249, 0x1000, v249
	v_lshlrev_b32_e32 v249, 6, v249
	v_readlane_b32 s16, v250, 46
	v_readlane_b32 s17, v250, 47
	s_nop 4
	global_load_dwordx4 v[164:167], v249, s[16:17]
	global_load_dwordx4 v[168:171], v249, s[16:17] offset:16
	global_load_dwordx4 v[196:199], v249, s[16:17] offset:32
	global_load_dwordx4 v[200:203], v249, s[16:17] offset:48
	s_or_b64 exec, exec, s[28:29]
.Lg_mlp1_nopf:
	v_writelane_b32 v255, s27, 43
	s_nop 7
	s_nop 7
	s_branch .LBB0_1601
